# v109: v106 + accumulator zeroing at unit boundaries done with v_mov_b64 pairs (252 pairs instead of 504 v_mov_b32)
# baseline (speedup 1.0000x reference)
; template <class Epi, class Sched, bool ALIGN_EPI, int LMASK = -1, int LMASKB = LMASK>
; __device__ __forceinline__ void gemm_phase(PG8_LAS unsigned char* lds, const Gemm g, const Sched& S, const Epi& E) {
;     ...
;         const bool has_next = S.next(ui + 1, nxt);
;         const char* nA = has_next ? (const char*)g.A + (size_t)(nxt.pm & LMASK) * tstepA : cA; const char* nB = has_next ? (const char*)g.Bt + (size_t)nxt.pm * g.b_pm_stride + (size_t)(nxt.pn & LMASKB) * tstepB : cB;
;     ...
;         for (int a = 0; a < 2; ++a)
; #pragma unroll
;             for (int b = 0; b < 2; ++b)
; #pragma unroll
;                 for (int m = 0; m < 4; ++m)
; #pragma unroll
;                     for (int n = 0; n < 2; ++n) acc[a][b][m][n] = (f32x4){0.f, 0.f, 0.f, 0.f};
;         cur = nxt; cA = nA; cB = nB; ++ui;
.LBB0_283:
	s_ashr_i32 s29, s28, 31
	s_lshl_b64 s[0:1], s[28:29], 21
	s_add_u32 s30, s39, s0
	s_addc_u32 s31, s40, s1
	s_and_b64 s[0:1], s[4:5], exec
	s_cselect_b32 s0, s31, s9
	s_cselect_b32 s1, s30, s8
	s_ashr_i32 s27, s26, 31
	s_lshl_b64 s[34:35], s[26:27], 21
	s_add_u32 s34, s41, s34
	s_addc_u32 s35, s42, s35
	s_and_b64 s[36:37], s[4:5], exec
	s_cselect_b32 s2, s35, s11
	s_cselect_b32 s7, s34, s10
	s_add_u32 s8, s8, 0x100800
	s_addc_u32 s9, s9, 0
	s_add_u32 s27, s10, 0x1000
	v_mov_b32_e32 v2, 0
	s_addc_u32 s29, s11, 0
	s_mov_b32 s54, -2
	v_mov_b32_e32 v3, v2
	v_mov_b64_e32 v[4:5], 0
	v_mov_b64_e32 v[6:7], 0
	v_mov_b64_e32 v[8:9], 0
	v_mov_b64_e32 v[10:11], 0
	v_mov_b64_e32 v[12:13], 0
	v_mov_b64_e32 v[18:19], 0
	v_mov_b64_e32 v[20:21], 0
	v_mov_b64_e32 v[26:27], 0
	v_mov_b64_e32 v[28:29], 0
	v_mov_b64_e32 v[34:35], 0
	v_mov_b64_e32 v[36:37], 0
	v_mov_b64_e32 v[42:43], 0
	v_mov_b64_e32 v[44:45], 0
	v_mov_b64_e32 v[50:51], 0
	v_mov_b64_e32 v[52:53], 0
	v_mov_b64_e32 v[14:15], 0
	v_mov_b64_e32 v[16:17], 0
	v_mov_b64_e32 v[22:23], 0
	v_mov_b64_e32 v[24:25], 0
	v_mov_b64_e32 v[30:31], 0
	v_mov_b64_e32 v[32:33], 0
	v_mov_b64_e32 v[38:39], 0
	v_mov_b64_e32 v[40:41], 0
	v_mov_b64_e32 v[46:47], 0
	v_mov_b64_e32 v[48:49], 0
	v_mov_b64_e32 v[54:55], 0
	v_mov_b64_e32 v[56:57], 0
	v_mov_b64_e32 v[58:59], 0
	v_mov_b64_e32 v[60:61], 0
	v_mov_b64_e32 v[62:63], 0
	v_mov_b64_e32 v[64:65], 0
	v_mov_b64_e32 v[66:67], 0
	v_mov_b64_e32 v[68:69], 0
	v_mov_b64_e32 v[70:71], 0
	v_mov_b64_e32 v[72:73], 0
	v_mov_b64_e32 v[74:75], 0
	v_mov_b64_e32 v[76:77], 0
	v_mov_b64_e32 v[82:83], 0
	v_mov_b64_e32 v[84:85], 0
	v_mov_b64_e32 v[90:91], 0
	v_mov_b64_e32 v[92:93], 0
	v_mov_b64_e32 v[98:99], 0
	v_mov_b64_e32 v[100:101], 0
	v_mov_b64_e32 v[106:107], 0
	v_mov_b64_e32 v[108:109], 0
	v_mov_b64_e32 v[114:115], 0
	v_mov_b64_e32 v[116:117], 0
	v_mov_b64_e32 v[78:79], 0
	v_mov_b64_e32 v[80:81], 0
	v_mov_b64_e32 v[86:87], 0
	v_mov_b64_e32 v[88:89], 0
	v_mov_b64_e32 v[94:95], 0
	v_mov_b64_e32 v[96:97], 0
	v_mov_b64_e32 v[102:103], 0
	v_mov_b64_e32 v[104:105], 0
	v_mov_b64_e32 v[110:111], 0
	v_mov_b64_e32 v[112:113], 0
	v_mov_b64_e32 v[118:119], 0
	v_mov_b64_e32 v[120:121], 0
	v_mov_b64_e32 v[122:123], 0
	v_mov_b64_e32 v[124:125], 0
	v_mov_b64_e32 v[126:127], 0
	v_mov_b64_e32 v[128:129], 0

; template <class Epi, class Sched, bool ALIGN_EPI, int LMASK = -1, int LMASKB = LMASK>
; __device__ __forceinline__ void gemm_phase(PG8_LAS unsigned char* lds, const Gemm g, const Sched& S, const Epi& E) {
;     ...
;         const bool has_next = S.next(ui + 1, nxt);
;         const char* nA = has_next ? (const char*)g.A + (size_t)(nxt.pm & LMASK) * tstepA : cA; const char* nB = has_next ? (const char*)g.Bt + (size_t)nxt.pm * g.b_pm_stride + (size_t)(nxt.pn & LMASKB) * tstepB : cB;
;     ...
;         for (int a = 0; a < 2; ++a)
; #pragma unroll
;             for (int b = 0; b < 2; ++b)
; #pragma unroll
;                 for (int m = 0; m < 4; ++m)
; #pragma unroll
;                     for (int n = 0; n < 2; ++n) acc[a][b][m][n] = (f32x4){0.f, 0.f, 0.f, 0.f};
;         cur = nxt; cA = nA; cB = nB; ++ui;
.LBB0_579:
	s_ashr_i32 s19, s18, 31
	s_lshl_b64 s[20:21], s[18:19], 21
	s_add_u32 s20, s2, s20
	s_addc_u32 s21, s3, s21
	s_and_b64 s[22:23], s[6:7], exec
	s_cselect_b32 s19, s21, s29
	s_cselect_b32 s25, s20, s28
	s_ashr_i32 s17, s16, 31
	s_lshl_b64 s[22:23], s[16:17], 21
	s_add_u32 s22, s36, s22
	s_addc_u32 s23, s37, s23
	s_and_b64 s[34:35], s[6:7], exec
	s_cselect_b32 s17, s23, s31
	s_cselect_b32 s47, s22, s30
	s_add_u32 s28, s28, 0x100800
	s_addc_u32 s29, s29, 0
	s_add_u32 s48, s30, 0x1000
	v_mov_b32_e32 v2, 0
	s_addc_u32 s49, s31, 0
	s_mov_b32 s50, -2
	s_waitcnt lgkmcnt(0)
	v_mov_b32_e32 v3, v2
	v_mov_b64_e32 v[4:5], 0
	v_mov_b64_e32 v[6:7], 0
	v_mov_b64_e32 v[8:9], 0
	v_mov_b64_e32 v[18:19], 0
	v_mov_b64_e32 v[20:21], 0
	v_mov_b64_e32 v[22:23], 0
	v_mov_b64_e32 v[24:25], 0
	v_mov_b64_e32 v[34:35], 0
	v_mov_b64_e32 v[36:37], 0
	v_mov_b64_e32 v[38:39], 0
	v_mov_b64_e32 v[40:41], 0
	v_mov_b64_e32 v[50:51], 0
	v_mov_b64_e32 v[52:53], 0
	v_mov_b64_e32 v[54:55], 0
	v_mov_b64_e32 v[56:57], 0
	v_mov_b64_e32 v[10:11], 0
	v_mov_b64_e32 v[12:13], 0
	v_mov_b64_e32 v[14:15], 0
	v_mov_b64_e32 v[16:17], 0
	v_mov_b64_e32 v[26:27], 0
	v_mov_b64_e32 v[28:29], 0
	v_mov_b64_e32 v[30:31], 0
	v_mov_b64_e32 v[32:33], 0
	v_mov_b64_e32 v[42:43], 0
	v_mov_b64_e32 v[44:45], 0
	v_mov_b64_e32 v[46:47], 0
	v_mov_b64_e32 v[48:49], 0
	v_mov_b64_e32 v[58:59], 0
	v_mov_b64_e32 v[60:61], 0
	v_mov_b64_e32 v[62:63], 0
	v_mov_b64_e32 v[64:65], 0
	v_mov_b64_e32 v[66:67], 0
	v_mov_b64_e32 v[68:69], 0
	v_mov_b64_e32 v[70:71], 0
	v_mov_b64_e32 v[72:73], 0
	v_mov_b64_e32 v[82:83], 0
	v_mov_b64_e32 v[84:85], 0
	v_mov_b64_e32 v[86:87], 0
	v_mov_b64_e32 v[88:89], 0
	v_mov_b64_e32 v[98:99], 0
	v_mov_b64_e32 v[100:101], 0
	v_mov_b64_e32 v[102:103], 0
	v_mov_b64_e32 v[104:105], 0
	v_mov_b64_e32 v[114:115], 0
	v_mov_b64_e32 v[116:117], 0
	v_mov_b64_e32 v[118:119], 0
	v_mov_b64_e32 v[120:121], 0
	v_mov_b64_e32 v[74:75], 0
	v_mov_b64_e32 v[76:77], 0
	v_mov_b64_e32 v[78:79], 0
	v_mov_b64_e32 v[80:81], 0
	v_mov_b64_e32 v[90:91], 0
	v_mov_b64_e32 v[92:93], 0
	v_mov_b64_e32 v[94:95], 0
	v_mov_b64_e32 v[96:97], 0
	v_mov_b64_e32 v[106:107], 0
	v_mov_b64_e32 v[108:109], 0
	v_mov_b64_e32 v[110:111], 0
	v_mov_b64_e32 v[112:113], 0
	v_mov_b64_e32 v[122:123], 0
	v_mov_b64_e32 v[124:125], 0
	v_mov_b64_e32 v[126:127], 0
	v_mov_b64_e32 v[128:129], 0

; template <class Epi, class Sched, bool ALIGN_EPI, int LMASK = -1, int LMASKB = LMASK>
; __device__ __forceinline__ void gemm_phase(PG8_LAS unsigned char* lds, const Gemm g, const Sched& S, const Epi& E) {
;     ...
;         const bool has_next = S.next(ui + 1, nxt);
;         const char* nA = has_next ? (const char*)g.A + (size_t)(nxt.pm & LMASK) * tstepA : cA; const char* nB = has_next ? (const char*)g.Bt + (size_t)nxt.pm * g.b_pm_stride + (size_t)(nxt.pn & LMASKB) * tstepB : cB;
;     ...
;         for (int a = 0; a < 2; ++a)
; #pragma unroll
;             for (int b = 0; b < 2; ++b)
; #pragma unroll
;                 for (int m = 0; m < 4; ++m)
; #pragma unroll
;                     for (int n = 0; n < 2; ++n) acc[a][b][m][n] = (f32x4){0.f, 0.f, 0.f, 0.f};
;         cur = nxt; cA = nA; cB = nB; ++ui;
.LBB0_677:
	s_ashr_i32 s17, s16, 31
	s_lshl_b64 s[18:19], s[16:17], 21
	s_add_u32 s18, s34, s18
	s_addc_u32 s19, s35, s19
	s_and_b64 s[20:21], s[4:5], exec
	s_cselect_b32 s1, s19, s25
	s_cselect_b32 s2, s18, s24
	s_ashr_i32 s15, s14, 31
	s_lshl_b64 s[20:21], s[14:15], 21
	s_add_u32 s20, s36, s20
	s_addc_u32 s21, s37, s21
	s_and_b64 s[28:29], s[4:5], exec
	s_cselect_b32 s15, s21, s27
	s_cselect_b32 s17, s20, s26
	s_add_u32 s24, s24, 0x100800
	s_addc_u32 s25, s25, 0
	s_add_u32 s47, s26, 0x1000
	v_mov_b32_e32 v2, 0
	s_addc_u32 s48, s27, 0
	s_mov_b32 s49, -2
	v_mov_b32_e32 v3, v2
	v_mov_b64_e32 v[4:5], 0
	v_mov_b64_e32 v[6:7], 0
	v_mov_b64_e32 v[8:9], 0
	v_mov_b64_e32 v[18:19], 0
	v_mov_b64_e32 v[20:21], 0
	v_mov_b64_e32 v[22:23], 0
	v_mov_b64_e32 v[24:25], 0
	v_mov_b64_e32 v[34:35], 0
	v_mov_b64_e32 v[36:37], 0
	v_mov_b64_e32 v[38:39], 0
	v_mov_b64_e32 v[40:41], 0
	v_mov_b64_e32 v[50:51], 0
	v_mov_b64_e32 v[52:53], 0
	v_mov_b64_e32 v[54:55], 0
	v_mov_b64_e32 v[56:57], 0
	v_mov_b64_e32 v[10:11], 0
	v_mov_b64_e32 v[12:13], 0
	v_mov_b64_e32 v[14:15], 0
	v_mov_b64_e32 v[16:17], 0
	v_mov_b64_e32 v[26:27], 0
	v_mov_b64_e32 v[28:29], 0
	v_mov_b64_e32 v[30:31], 0
	v_mov_b64_e32 v[32:33], 0
	v_mov_b64_e32 v[42:43], 0
	v_mov_b64_e32 v[44:45], 0
	v_mov_b64_e32 v[46:47], 0
	v_mov_b64_e32 v[48:49], 0
	v_mov_b64_e32 v[58:59], 0
	v_mov_b64_e32 v[60:61], 0
	v_mov_b64_e32 v[62:63], 0
	v_mov_b64_e32 v[64:65], 0
	v_mov_b64_e32 v[66:67], 0
	v_mov_b64_e32 v[68:69], 0
	v_mov_b64_e32 v[70:71], 0
	v_mov_b64_e32 v[72:73], 0
	v_mov_b64_e32 v[82:83], 0
	v_mov_b64_e32 v[84:85], 0
	v_mov_b64_e32 v[86:87], 0
	v_mov_b64_e32 v[88:89], 0
	v_mov_b64_e32 v[98:99], 0
	v_mov_b64_e32 v[100:101], 0
	v_mov_b64_e32 v[102:103], 0
	v_mov_b64_e32 v[104:105], 0
	v_mov_b64_e32 v[114:115], 0
	v_mov_b64_e32 v[116:117], 0
	v_mov_b64_e32 v[118:119], 0
	v_mov_b64_e32 v[120:121], 0
	v_mov_b64_e32 v[74:75], 0
	v_mov_b64_e32 v[76:77], 0
	v_mov_b64_e32 v[78:79], 0
	v_mov_b64_e32 v[80:81], 0
	v_mov_b64_e32 v[90:91], 0
	v_mov_b64_e32 v[92:93], 0
	v_mov_b64_e32 v[94:95], 0
	v_mov_b64_e32 v[96:97], 0
	v_mov_b64_e32 v[106:107], 0
	v_mov_b64_e32 v[108:109], 0
	v_mov_b64_e32 v[110:111], 0
	v_mov_b64_e32 v[112:113], 0
	v_mov_b64_e32 v[122:123], 0
	v_mov_b64_e32 v[124:125], 0
	v_mov_b64_e32 v[126:127], 0
	v_mov_b64_e32 v[128:129], 0

; template <class Epi, class Sched, bool ALIGN_EPI, int LMASK = -1, int LMASKB = LMASK>
; __device__ __forceinline__ void gemm_phase(PG8_LAS unsigned char* lds, const Gemm g, const Sched& S, const Epi& E) {
;     ...
;         const bool has_next = S.next(ui + 1, nxt);
;         const char* nA = has_next ? (const char*)g.A + (size_t)(nxt.pm & LMASK) * tstepA : cA; const char* nB = has_next ? (const char*)g.Bt + (size_t)nxt.pm * g.b_pm_stride + (size_t)(nxt.pn & LMASKB) * tstepB : cB;
;     ...
;         for (int a = 0; a < 2; ++a)
; #pragma unroll
;             for (int b = 0; b < 2; ++b)
; #pragma unroll
;                 for (int m = 0; m < 4; ++m)
; #pragma unroll
;                     for (int n = 0; n < 2; ++n) acc[a][b][m][n] = (f32x4){0.f, 0.f, 0.f, 0.f};
;         cur = nxt; cA = nA; cB = nB; ++ui;
.LBB0_760:
	s_ashr_i32 s19, s18, 31
	s_lshl_b64 s[2:3], s[18:19], 23
	s_add_u32 s20, s34, s2
	s_addc_u32 s21, s35, s3
	s_and_b64 s[2:3], s[6:7], exec
	s_cselect_b32 s19, s21, s29
	s_cselect_b32 s46, s20, s28
	s_ashr_i32 s17, s16, 31
	s_lshl_b64 s[2:3], s[16:17], 23
	s_add_u32 s22, s36, s2
	s_addc_u32 s23, s37, s3
	s_and_b64 s[2:3], s[6:7], exec
	s_cselect_b32 s17, s23, s31
	s_cselect_b32 s47, s22, s30
	s_add_u32 s28, s28, 0x400800
	s_addc_u32 s29, s29, 0
	s_add_u32 s48, s30, 0x1000
	v_mov_b32_e32 v2, 0
	s_addc_u32 s49, s31, 0
	s_mov_b32 s50, -2
	s_waitcnt lgkmcnt(0)
	v_mov_b32_e32 v3, v2
	v_mov_b64_e32 v[4:5], 0
	v_mov_b64_e32 v[6:7], 0
	v_mov_b64_e32 v[8:9], 0
	v_mov_b64_e32 v[18:19], 0
	v_mov_b64_e32 v[20:21], 0
	v_mov_b64_e32 v[22:23], 0
	v_mov_b64_e32 v[24:25], 0
	v_mov_b64_e32 v[34:35], 0
	v_mov_b64_e32 v[36:37], 0
	v_mov_b64_e32 v[38:39], 0
	v_mov_b64_e32 v[40:41], 0
	v_mov_b64_e32 v[50:51], 0
	v_mov_b64_e32 v[52:53], 0
	v_mov_b64_e32 v[54:55], 0
	v_mov_b64_e32 v[56:57], 0
	v_mov_b64_e32 v[10:11], 0
	v_mov_b64_e32 v[12:13], 0
	v_mov_b64_e32 v[14:15], 0
	v_mov_b64_e32 v[16:17], 0
	v_mov_b64_e32 v[26:27], 0
	v_mov_b64_e32 v[28:29], 0
	v_mov_b64_e32 v[30:31], 0
	v_mov_b64_e32 v[32:33], 0
	v_mov_b64_e32 v[42:43], 0
	v_mov_b64_e32 v[44:45], 0
	v_mov_b64_e32 v[46:47], 0
	v_mov_b64_e32 v[48:49], 0
	v_mov_b64_e32 v[58:59], 0
	v_mov_b64_e32 v[60:61], 0
	v_mov_b64_e32 v[62:63], 0
	v_mov_b64_e32 v[64:65], 0
	v_mov_b64_e32 v[66:67], 0
	v_mov_b64_e32 v[68:69], 0
	v_mov_b64_e32 v[70:71], 0
	v_mov_b64_e32 v[72:73], 0
	v_mov_b64_e32 v[82:83], 0
	v_mov_b64_e32 v[84:85], 0
	v_mov_b64_e32 v[86:87], 0
	v_mov_b64_e32 v[88:89], 0
	v_mov_b64_e32 v[98:99], 0
	v_mov_b64_e32 v[100:101], 0
	v_mov_b64_e32 v[102:103], 0
	v_mov_b64_e32 v[104:105], 0
	v_mov_b64_e32 v[114:115], 0
	v_mov_b64_e32 v[116:117], 0
	v_mov_b64_e32 v[118:119], 0
	v_mov_b64_e32 v[120:121], 0
	v_mov_b64_e32 v[74:75], 0
	v_mov_b64_e32 v[76:77], 0
	v_mov_b64_e32 v[78:79], 0
	v_mov_b64_e32 v[80:81], 0
	v_mov_b64_e32 v[90:91], 0
	v_mov_b64_e32 v[92:93], 0
	v_mov_b64_e32 v[94:95], 0
	v_mov_b64_e32 v[96:97], 0
	v_mov_b64_e32 v[106:107], 0
	v_mov_b64_e32 v[108:109], 0
	v_mov_b64_e32 v[110:111], 0
	v_mov_b64_e32 v[112:113], 0
	v_mov_b64_e32 v[122:123], 0
	v_mov_b64_e32 v[124:125], 0
	v_mov_b64_e32 v[126:127], 0
	v_mov_b64_e32 v[128:129], 0
